# RG-LRU gate fused behind the LRU units per workgroup (own rows/channels, workgroup barrier); grid barrier between them skipped
# speedup vs baseline: 1.0260x; 1.0075x over previous
.LBB0_308:
	s_mov_b64 s[6:7], s[26:27]
	s_getreg_b32 s8, hwreg(HW_REG_XCC_ID, 0, 4)
	s_waitcnt vmcnt(0)
	s_barrier
	s_mov_b64 s[4:5], exec
	v_readlane_b32 s10, v254, 0
	v_readlane_b32 s11, v254, 1
	s_mov_b64 s[10:11], 0
	s_mov_b64 exec, s[10:11]
	s_cbranch_execz .LBB0_361
	v_readlane_b32 s9, v254, 36
	s_waitcnt vmcnt(0) expcnt(0) lgkmcnt(0)
	s_and_b32 s18, s8, 15
	v_mov_b32_e32 v1, s9
	ds_read_b32 v3, v1
	v_readlane_b32 s9, v254, 37
	s_waitcnt lgkmcnt(0)
	v_cmp_ne_u32_e32 vcc, 0, v3
	v_mov_b32_e32 v1, s9
	ds_read_b32 v2, v1
	s_cbranch_vccnz .LBB0_325
	s_add_u32 s8, s6, 0x10200
	s_addc_u32 s9, s7, 0
	s_add_u32 s10, s6, 0x10400
	s_addc_u32 s11, s7, 0
	s_add_u32 s12, s6, 0x10500
	s_addc_u32 s13, s7, 0
	s_add_u32 s14, s6, 0x10600
	s_addc_u32 s15, s7, 0
	s_add_u32 s16, s6, 0x10700
	s_addc_u32 s17, s7, 0
	s_add_u32 s20, s6, 0x10800
	s_addc_u32 s21, s7, 0
	s_add_u32 s22, s6, 0x10900
	s_addc_u32 s23, s7, 0
	s_add_u32 s28, s6, 0x10a00
	s_addc_u32 s29, s7, 0
	s_add_u32 s34, s6, 0x10b00
	s_addc_u32 s35, s7, 0
	s_add_u32 s38, s6, 0x10c00
	s_addc_u32 s39, s7, 0
	s_add_u32 s40, s6, 0x10d00
	s_addc_u32 s41, s7, 0
	s_add_u32 s42, s6, 0x10e00
	s_addc_u32 s43, s7, 0
	s_add_u32 s48, s6, 0x10f00
	s_addc_u32 s49, s7, 0
	s_add_u32 s50, s6, 0x11000
	s_addc_u32 s51, s7, 0
	s_add_u32 s52, s6, 0x11100
	s_addc_u32 s53, s7, 0
	s_add_u32 s56, s6, 0x11200
	s_addc_u32 s57, s7, 0
	s_add_u32 s58, s6, 0x11300
	s_addc_u32 s59, s7, 0
	s_mov_b32 s19, 1
	s_branch .LBB0_313

.LBB0_361:
	s_or_b64 exec, exec, s[4:5]
	s_mov_b64 s[6:7], s[26:27]
	s_mov_b64 s[8:9], s[26:27]
	s_mov_b64 s[10:11], s[26:27]
	s_mov_b64 s[12:13], s[26:27]
	s_waitcnt lgkmcnt(0)
	v_mov_b32_e32 v2, v179
	v_readlane_b32 s4, v254, 5
	s_barrier
	s_nop 0
	v_add_u32_e32 v1, s4, v2
	v_cmp_gt_i32_e32 vcc, s49, v1
	s_and_saveexec_b64 s[4:5], vcc
	s_cbranch_execz .LBB0_364
	s_add_u32 s6, s6, 0x7100000
	s_addc_u32 s7, s7, 0
	s_add_u32 s8, s8, 0x9100000
	s_addc_u32 s9, s9, 0
	s_add_u32 s10, s10, 0xb100000
	s_addc_u32 s11, s11, 0
	s_add_u32 s12, s12, 0x16100000
	s_addc_u32 s13, s13, 0
	v_readlane_b32 s17, v254, 2
	s_nop 0
	s_cmpk_lt_i32 s17, 0x100
	s_cbranch_scc0 .LBB0_364
.Lgate_bun:
	s_cmpk_lt_i32 s17, 0x80
	s_cbranch_scc0 .Lgate_prompt
	s_lshr_b32 s20, s17, 4
	s_and_b32 s21, s17, 15
	s_lshl_b32 s20, s20, 10
	s_addk_i32 s20, 0x2000
	s_lshl_b32 s20, s20, 7
	s_lshl_b32 s21, s21, 3
	s_add_i32 s20, s20, s21
	v_lshrrev_b32_e32 v1, 3, v179
	v_and_b32_e32 v3, 7, v179
	v_lshl_or_b32 v1, v1, 7, v3
	s_movk_i32 s18, 0x2000
	s_branch .Lgate_go
.Lgate_prompt:
	s_add_i32 s20, s17, 0xffffff80
	s_lshr_b32 s21, s20, 2
	s_and_b32 s20, s20, 3
	s_lshl_b32 s20, s20, 5
	s_lshl_b32 s21, s21, 15
	s_add_i32 s20, s20, s21
	v_lshrrev_b32_e32 v1, 5, v179
	v_and_b32_e32 v3, 31, v179
	v_lshl_or_b32 v1, v1, 7, v3
	s_movk_i32 s18, 0x800
.Lgate_go:
	v_add_u32_e32 v1, s20, v1
	v_lshlrev_b32_e32 v2, 3, v1
	s_mov_b32 s19, 16
.LBB0_363:
	s_waitcnt vmcnt(3)
	v_ashrrev_i32_e32 v12, 7, v1
	v_ashrrev_i32_e32 v13, 31, v12
	v_and_b32_e32 v3, 0x3f8, v2
	v_lshlrev_b64 v[16:17], 11, v[12:13]
	v_lshlrev_b64 v[12:13], 12, v[12:13]
	v_lshlrev_b32_e32 v18, 1, v3
	v_mov_b32_e32 v19, v0
	v_lshl_add_u64 v[12:13], s[10:11], 0, v[12:13]
	v_lshl_add_u64 v[12:13], v[12:13], 0, v[18:19]
	v_lshl_add_u64 v[4:5], s[6:7], 0, v[16:17]
	global_load_dwordx4 v[12:15], v[12:13], off
	v_lshl_add_u64 v[4:5], v[4:5], 0, v[18:19]
	global_load_dwordx4 v[4:7], v[4:5], off
	v_lshl_add_u64 v[8:9], s[8:9], 0, v[16:17]
	v_lshl_add_u64 v[8:9], v[8:9], 0, v[18:19]
	global_load_dwordx4 v[8:11], v[8:9], off
	v_add_u32_e32 v1, s18, v1
	s_waitcnt vmcnt(2)
	v_lshlrev_b32_e32 v24, 16, v12
	v_mul_f32_e32 v3, 0x3d372713, v24
	s_waitcnt vmcnt(1)
	v_lshlrev_b32_e32 v20, 16, v4
	v_and_b32_e32 v21, 0xffff0000, v4
	v_mul_f32_e32 v3, v3, v24
	v_mov_b32_e32 v4, v24
	v_fmac_f32_e32 v4, v3, v4
	v_mul_f32_e32 v3, 0x3f4c422a, v4
	v_mul_f32_e32 v3, -2.0, v3
	v_mul_f32_e32 v3, 0x3fb8aa3b, v3
	v_exp_f32_e32 v3, v3
	v_and_b32_e32 v25, 0xffff0000, v12
	v_mov_b32_e32 v4, v25
	s_waitcnt vmcnt(0)
	v_lshlrev_b32_e32 v22, 16, v8
	v_add_f32_e32 v3, 1.0, v3
	v_rcp_f32_e32 v26, v3
	v_mul_f32_e32 v3, 0x3d372713, v25
	v_mul_f32_e32 v3, v3, v25
	v_fmac_f32_e32 v4, v3, v4
	v_mul_f32_e32 v3, 0x3f4c422a, v4
	v_mul_f32_e32 v3, -2.0, v3
	v_mul_f32_e32 v3, 0x3fb8aa3b, v3
	v_exp_f32_e32 v3, v3
	v_and_b32_e32 v23, 0xffff0000, v8
	v_lshlrev_b32_e32 v12, 16, v13
	v_pk_add_f32 v[20:21], v[20:21], v[22:23]
	v_add_f32_e32 v3, 1.0, v3
	v_rcp_f32_e32 v27, v3
	v_mul_f32_e32 v3, 0x3d372713, v12
	v_mul_f32_e32 v3, v3, v12
	v_and_b32_e32 v13, 0xffff0000, v13
	v_pk_mul_f32 v[22:23], v[26:27], v[24:25]
	v_lshlrev_b32_e32 v4, 16, v5
	v_pk_mul_f32 v[20:21], v[20:21], v[22:23]
	v_mov_b32_e32 v22, v12
	v_fmac_f32_e32 v22, v3, v22
	v_mul_f32_e32 v3, 0x3f4c422a, v22
	v_mul_f32_e32 v3, -2.0, v3
	v_mul_f32_e32 v3, 0x3fb8aa3b, v3
	v_exp_f32_e32 v3, v3
	v_and_b32_e32 v5, 0xffff0000, v5
	v_lshlrev_b32_e32 v8, 16, v9
	v_and_b32_e32 v9, 0xffff0000, v9
	v_add_f32_e32 v3, 1.0, v3
	v_rcp_f32_e32 v22, v3
	v_mul_f32_e32 v3, 0x3d372713, v13
	v_pk_add_f32 v[4:5], v[4:5], v[8:9]
	v_mul_f32_e32 v3, v3, v13
	v_mov_b32_e32 v8, v13
	v_fmac_f32_e32 v8, v3, v8
	v_mul_f32_e32 v3, 0x3f4c422a, v8
	v_mul_f32_e32 v3, -2.0, v3
	v_mul_f32_e32 v3, 0x3fb8aa3b, v3
	v_exp_f32_e32 v3, v3
	s_nop 0
	v_add_f32_e32 v3, 1.0, v3
	v_rcp_f32_e32 v23, v3
	s_nop 0
	v_pk_mul_f32 v[8:9], v[22:23], v[12:13]
	v_lshlrev_b32_e32 v22, 16, v14
	v_mul_f32_e32 v3, 0x3d372713, v22
	v_pk_mul_f32 v[8:9], v[4:5], v[8:9]
	v_lshlrev_b32_e32 v4, 16, v6
	v_and_b32_e32 v5, 0xffff0000, v6
	v_mul_f32_e32 v3, v3, v22
	v_mov_b32_e32 v6, v22
	v_fmac_f32_e32 v6, v3, v6
	v_mul_f32_e32 v3, 0x3f4c422a, v6
	v_mul_f32_e32 v3, -2.0, v3
	v_mul_f32_e32 v3, 0x3fb8aa3b, v3
	v_exp_f32_e32 v3, v3
	v_and_b32_e32 v23, 0xffff0000, v14
	v_mov_b32_e32 v6, v23
	v_lshlrev_b32_e32 v12, 16, v10
	v_add_f32_e32 v3, 1.0, v3
	v_rcp_f32_e32 v24, v3
	v_mul_f32_e32 v3, 0x3d372713, v23
	v_mul_f32_e32 v3, v3, v23
	v_fmac_f32_e32 v6, v3, v6
	v_mul_f32_e32 v3, 0x3f4c422a, v6
	v_mul_f32_e32 v3, -2.0, v3
	v_mul_f32_e32 v3, 0x3fb8aa3b, v3
	v_exp_f32_e32 v3, v3
	v_and_b32_e32 v13, 0xffff0000, v10
	v_lshlrev_b32_e32 v10, 16, v15
	v_mov_b32_e32 v14, v10
	v_add_f32_e32 v3, 1.0, v3
	v_rcp_f32_e32 v25, v3
	v_mul_f32_e32 v3, 0x3d372713, v10
	v_mul_f32_e32 v3, v3, v10
	v_fmac_f32_e32 v14, v3, v14
	v_mul_f32_e32 v3, 0x3f4c422a, v14
	v_mul_f32_e32 v3, -2.0, v3
	v_mul_f32_e32 v3, 0x3fb8aa3b, v3
	v_exp_f32_e32 v3, v3
	v_pk_add_f32 v[4:5], v[4:5], v[12:13]
	v_pk_mul_f32 v[12:13], v[24:25], v[22:23]
	v_lshlrev_b32_e32 v6, 16, v11
	v_pk_mul_f32 v[12:13], v[4:5], v[12:13]
	v_lshlrev_b32_e32 v4, 16, v7
	v_and_b32_e32 v5, 0xffff0000, v7
	v_and_b32_e32 v7, 0xffff0000, v11
	v_and_b32_e32 v11, 0xffff0000, v15
	v_add_f32_e32 v3, 1.0, v3
	v_rcp_f32_e32 v14, v3
	v_mul_f32_e32 v3, 0x3d372713, v11
	v_pk_add_f32 v[4:5], v[4:5], v[6:7]
	v_mul_f32_e32 v3, v3, v11
	v_mov_b32_e32 v6, v11
	v_fmac_f32_e32 v6, v3, v6
	v_mul_f32_e32 v3, 0x3f4c422a, v6
	v_mul_f32_e32 v3, -2.0, v3
	v_mul_f32_e32 v3, 0x3fb8aa3b, v3
	v_exp_f32_e32 v3, v3
	s_nop 0
	v_add_f32_e32 v3, 1.0, v3
	v_rcp_f32_e32 v15, v3
	s_nop 0
	v_pk_mul_f32 v[6:7], v[14:15], v[10:11]
	s_nop 0
	v_pk_mul_f32 v[10:11], v[4:5], v[6:7]
	v_cvt_pk_bf16_f32 v5, v8, v9
	v_lshl_add_u64 v[8:9], s[12:13], 0, v[16:17]
	v_cvt_pk_bf16_f32 v4, v20, v21
	v_cvt_pk_bf16_f32 v6, v12, v13
	v_cvt_pk_bf16_f32 v7, v10, v11
	v_lshl_add_u64 v[8:9], v[8:9], 0, v[18:19]
	global_store_dwordx4 v[8:9], v[4:7], off
	s_add_i32 s19, s19, -1
	s_cmp_lg_u32 s19, 0
	s_cbranch_scc1 .LBB0_363
	s_add_i32 s17, s17, s74
	s_cmpk_lt_i32 s17, 0x100
	s_cbranch_scc1 .Lgate_bun
